# v12 + QK^T block: K fragments read two k-steps ahead on the four LDS buffers, rope q fragments read 2+ steps ahead
# speedup vs baseline: 1.0185x; 1.0085x over previous
.LBB0_894:
	s_bitcmp1_b32 s1, 0
	s_cselect_b32 s0, 0x6400, 0
	v_add_u32_e32 v2, s0, v245
	ds_read_b128 v[4:7], v2
	ds_read_b128 v[8:11], v2 offset:12800
	ds_read_b128 v[12:15], v2 offset:32
	ds_read_b128 v[176:179], v2 offset:12832
	s_waitcnt lgkmcnt(3)
	v_mfma_f32_32x32x16_bf16 v[98:113], v[4:7], v[154:157], 0
	s_waitcnt lgkmcnt(2)
	v_mfma_f32_32x32x16_bf16 v[82:97], v[8:11], v[154:157], 0
	ds_read_b128 v[4:7], v2 offset:64
	ds_read_b128 v[8:11], v2 offset:12864
	s_waitcnt lgkmcnt(3)
	v_mfma_f32_32x32x16_bf16 v[98:113], v[12:15], v[126:129], v[98:113]
	s_waitcnt lgkmcnt(2)
	v_mfma_f32_32x32x16_bf16 v[82:97], v[176:179], v[126:129], v[82:97]
	ds_read_b128 v[12:15], v2 offset:96
	ds_read_b128 v[176:179], v2 offset:12896
	s_waitcnt lgkmcnt(3)
	v_mfma_f32_32x32x16_bf16 v[98:113], v[4:7], v[130:133], v[98:113]
	s_waitcnt lgkmcnt(2)
	v_mfma_f32_32x32x16_bf16 v[82:97], v[8:11], v[130:133], v[82:97]
	ds_read_b128 v[4:7], v2 offset:128
	ds_read_b128 v[8:11], v2 offset:12928
	s_waitcnt lgkmcnt(3)
	v_mfma_f32_32x32x16_bf16 v[98:113], v[12:15], v[134:137], v[98:113]
	s_waitcnt lgkmcnt(2)
	v_mfma_f32_32x32x16_bf16 v[82:97], v[176:179], v[134:137], v[82:97]
	ds_read_b128 v[12:15], v2 offset:160
	ds_read_b128 v[176:179], v2 offset:12960
	s_waitcnt lgkmcnt(3)
	v_mfma_f32_32x32x16_bf16 v[98:113], v[4:7], v[138:141], v[98:113]
	s_waitcnt lgkmcnt(2)
	v_mfma_f32_32x32x16_bf16 v[82:97], v[8:11], v[138:141], v[82:97]
	ds_read_b128 v[4:7], v2 offset:192
	ds_read_b128 v[8:11], v2 offset:12992
	s_waitcnt lgkmcnt(3)
	v_mfma_f32_32x32x16_bf16 v[98:113], v[12:15], v[142:145], v[98:113]
	s_waitcnt lgkmcnt(2)
	v_mfma_f32_32x32x16_bf16 v[82:97], v[176:179], v[142:145], v[82:97]
	ds_read_b128 v[12:15], v2 offset:224
	ds_read_b128 v[176:179], v2 offset:13024
	s_waitcnt lgkmcnt(3)
	v_mfma_f32_32x32x16_bf16 v[98:113], v[4:7], v[150:153], v[98:113]
	s_waitcnt lgkmcnt(2)
	v_mfma_f32_32x32x16_bf16 v[82:97], v[8:11], v[150:153], v[82:97]
	ds_read_b128 v[4:7], v2 offset:256
	ds_read_b128 v[8:11], v2 offset:13056
	s_waitcnt lgkmcnt(3)
	v_mfma_f32_32x32x16_bf16 v[98:113], v[12:15], v[118:121], v[98:113]
	s_waitcnt lgkmcnt(2)
	v_mfma_f32_32x32x16_bf16 v[82:97], v[176:179], v[118:121], v[82:97]
	ds_read_b128 v[12:15], v249
	ds_read_b128 v[176:179], v249 offset:1024
	s_waitcnt lgkmcnt(1)
	v_mfma_f32_32x32x16_bf16 v[98:113], v[4:7], v[12:15], v[98:113]
	ds_read_b128 v[4:7], v2 offset:288
	v_mfma_f32_32x32x16_bf16 v[82:97], v[8:11], v[12:15], v[82:97]
	ds_read_b128 v[8:11], v2 offset:13088
	ds_read_b128 v[12:15], v249 offset:2048
	s_waitcnt lgkmcnt(2)
	v_mfma_f32_32x32x16_bf16 v[98:113], v[4:7], v[176:179], v[98:113]
	ds_read_b128 v[4:7], v2 offset:320
	s_waitcnt lgkmcnt(2)
	v_mfma_f32_32x32x16_bf16 v[82:97], v[8:11], v[176:179], v[82:97]
	ds_read_b128 v[8:11], v2 offset:13120
	ds_read_b128 v[176:179], v249 offset:3072
	s_waitcnt lgkmcnt(2)
	v_mfma_f32_32x32x16_bf16 v[98:113], v[4:7], v[12:15], v[98:113]
	ds_read_b128 v[4:7], v2 offset:352
	s_waitcnt lgkmcnt(2)
	v_mfma_f32_32x32x16_bf16 v[82:97], v[8:11], v[12:15], v[82:97]
	ds_read_b128 v[8:11], v2 offset:13152
	s_waitcnt lgkmcnt(1)
	v_mfma_f32_32x32x16_bf16 v[98:113], v[4:7], v[176:179], v[98:113]
	s_waitcnt lgkmcnt(0)
	v_mfma_f32_32x32x16_bf16 v[82:97], v[8:11], v[176:179], v[82:97]
	s_add_i32 s0, s92, 63
	s_cmp_le_u32 s0, s3
	s_cbranch_scc1 .LBB0_896
	v_mov_b32_e32 v2, v251
	s_nop 0
	v_cmp_gt_i32_e64 s[60:61], 22, v2
	v_cmp_gt_i32_e64 s[62:63], 23, v2
	v_cmp_gt_i32_e64 s[58:59], 21, v2
	s_and_b64 s[60:61], s[62:63], s[60:61]
	v_cmp_gt_i32_e64 s[56:57], 20, v2
	s_and_b64 s[58:59], s[60:61], s[58:59]
	v_cmp_gt_i32_e64 s[54:55], 19, v2
	s_and_b64 s[56:57], s[58:59], s[56:57]
	v_cmp_gt_i32_e64 s[52:53], 18, v2
	s_and_b64 s[54:55], s[56:57], s[54:55]
	v_cmp_gt_i32_e64 s[50:51], 17, v2
	s_and_b64 s[52:53], s[54:55], s[52:53]
	v_cmp_gt_i32_e64 s[48:49], 16, v2
	s_and_b64 s[50:51], s[52:53], s[50:51]
	v_cmp_gt_i32_e64 s[46:47], 7, v2
	s_and_b64 s[48:49], s[50:51], s[48:49]
	v_cmp_gt_i32_e64 s[44:45], 6, v2
	s_and_b64 s[46:47], s[48:49], s[46:47]
	v_cmp_gt_i32_e64 s[42:43], 5, v2
	s_and_b64 s[44:45], s[46:47], s[44:45]
	v_cmp_gt_i32_e64 s[40:41], 4, v2
	s_and_b64 s[42:43], s[44:45], s[42:43]
	v_cmp_gt_i32_e64 s[38:39], 3, v2
	s_and_b64 s[40:41], s[42:43], s[40:41]
	v_cmp_gt_i32_e64 s[36:37], 2, v2
	s_and_b64 s[38:39], s[40:41], s[38:39]
	v_cmp_gt_i32_e64 s[34:35], 1, v2
	s_and_b64 s[36:37], s[38:39], s[36:37]
	v_cmp_gt_i32_e64 s[30:31], 0, v2
	s_and_b64 s[34:35], s[36:37], s[34:35]
	s_and_b64 s[30:31], s[34:35], s[30:31]
	v_cmp_gt_i32_e64 s[26:27], 54, v2
	v_cndmask_b32_e64 v98, v98, v248, s[30:31]
	v_cmp_gt_i32_e64 s[30:31], 55, v2
	v_cmp_gt_i32_e64 s[24:25], 53, v2
	s_and_b64 s[26:27], s[30:31], s[26:27]
	v_cmp_gt_i32_e64 s[22:23], 52, v2
	s_and_b64 s[24:25], s[26:27], s[24:25]
	v_cmp_gt_i32_e64 s[20:21], 51, v2
	s_and_b64 s[22:23], s[24:25], s[22:23]
	v_cmp_gt_i32_e64 s[18:19], 50, v2
	s_and_b64 s[20:21], s[22:23], s[20:21]
	v_cmp_gt_i32_e64 s[16:17], 49, v2
	s_and_b64 s[18:19], s[20:21], s[18:19]
	v_cmp_gt_i32_e64 s[14:15], 48, v2
	s_and_b64 s[16:17], s[18:19], s[16:17]
	v_cmp_gt_i32_e64 s[12:13], 39, v2
	s_and_b64 s[14:15], s[16:17], s[14:15]
	v_cmp_gt_i32_e64 s[10:11], 38, v2
	s_and_b64 s[12:13], s[14:15], s[12:13]
	v_cmp_gt_i32_e64 s[8:9], 37, v2
	s_and_b64 s[10:11], s[12:13], s[10:11]
	v_cmp_gt_i32_e64 s[6:7], 36, v2
	s_and_b64 s[8:9], s[10:11], s[8:9]
	v_cmp_gt_i32_e64 s[4:5], 35, v2
	s_and_b64 s[6:7], s[8:9], s[6:7]
	v_cmp_gt_i32_e64 s[28:29], 34, v2
	s_and_b64 s[4:5], s[6:7], s[4:5]
	v_cmp_gt_i32_e64 s[0:1], 33, v2
	v_cndmask_b32_e64 v85, v85, v248, s[4:5]
	s_and_b64 s[4:5], s[4:5], s[28:29]
	v_cmp_gt_i32_e32 vcc, 32, v2
	s_and_b64 s[0:1], s[4:5], s[0:1]
	s_and_b64 vcc, s[0:1], vcc
	v_cndmask_b32_e64 v113, v113, v248, s[62:63]
	v_cndmask_b32_e64 v112, v112, v248, s[60:61]
	v_cndmask_b32_e64 v111, v111, v248, s[58:59]
	v_cndmask_b32_e64 v110, v110, v248, s[56:57]
	v_cndmask_b32_e64 v109, v109, v248, s[54:55]
	v_cndmask_b32_e64 v108, v108, v248, s[52:53]
	v_cndmask_b32_e64 v107, v107, v248, s[50:51]
	v_cndmask_b32_e64 v106, v106, v248, s[48:49]
	v_cndmask_b32_e64 v105, v105, v248, s[46:47]
	v_cndmask_b32_e64 v104, v104, v248, s[44:45]
	v_cndmask_b32_e64 v103, v103, v248, s[42:43]
	v_cndmask_b32_e64 v102, v102, v248, s[40:41]
	v_cndmask_b32_e64 v101, v101, v248, s[38:39]
	v_cndmask_b32_e64 v100, v100, v248, s[36:37]
	v_cndmask_b32_e64 v99, v99, v248, s[34:35]
	v_cndmask_b32_e64 v97, v97, v248, s[30:31]
	v_cndmask_b32_e64 v96, v96, v248, s[26:27]
	v_cndmask_b32_e64 v95, v95, v248, s[24:25]
	v_cndmask_b32_e64 v94, v94, v248, s[22:23]
	v_cndmask_b32_e64 v93, v93, v248, s[20:21]
	v_cndmask_b32_e64 v92, v92, v248, s[18:19]
	v_cndmask_b32_e64 v91, v91, v248, s[16:17]
	v_cndmask_b32_e64 v90, v90, v248, s[14:15]
	v_cndmask_b32_e64 v89, v89, v248, s[12:13]
	v_cndmask_b32_e64 v88, v88, v248, s[10:11]
	v_cndmask_b32_e64 v87, v87, v248, s[8:9]
	v_cndmask_b32_e64 v86, v86, v248, s[6:7]
	v_cndmask_b32_e64 v84, v84, v248, s[4:5]
	v_cndmask_b32_e64 v83, v83, v248, s[0:1]
	v_cndmask_b32_e32 v82, v82, v248, vcc
